# P0 converts only w_in(0,1)+w_out(0); w_in(l+2), w_out(l+1) converted at attention(l) start by the first 1024 waves (128 WGs), published by the next grid barrier
# speedup vs baseline: 1.0265x; 1.0086x over previous
.LBB0_5:
	s_or_b64 exec, exec, s[4:5]
	s_lshr_b32 s4, s8, 6
	s_load_dwordx2 s[8:9], s[0:1], 0x50
	v_readlane_b32 s5, v255, 0
	s_lshl_b32 s5, s5, 3
	s_add_i32 s6, s4, s5
	s_load_dwordx16 s[80:95], s[0:1], 0x0
	s_waitcnt lgkmcnt(0)
	s_lshl_b32 s8, s8, 3
	s_add_u32 s5, s56, 0x100000
	v_writelane_b32 v255, s5, 6
	s_addc_u32 s5, s57, 0
	v_writelane_b32 v255, s5, 7
	s_add_u32 s5, s56, 0x8100000
	v_writelane_b32 v255, s5, 8
	s_addc_u32 s5, s57, 0
	v_writelane_b32 v255, s5, 9
	v_writelane_b32 v255, s84, 53
	v_writelane_b32 v255, s85, 54
	v_writelane_b32 v255, s82, 57
	v_writelane_b32 v255, s83, 58
	v_writelane_b32 v255, s6, 59
	v_writelane_b32 v255, s92, 60
	v_writelane_b32 v255, s93, 61
	s_cmp_gt_i32 s6, 0x9fff
	v_and_b32_e32 v1, 63, v243
	s_cbranch_scc1 .LBB0_20
	v_lshrrev_b32_e32 v6, 3, v1
	v_and_b32_e32 v7, 7, v1
	v_lshlrev_b32_e32 v8, 4, v7
	v_lshl_or_b32 v2, v6, 18, v8
	v_lshl_or_b32 v3, v6, 16, v8
	v_lshlrev_b32_e32 v4, 5, v6
	v_lshlrev_b32_e32 v9, 4, v6
	v_lshl_or_b32 v5, v7, 14, v9
	v_readlane_b32 s40, v255, 6
	v_readlane_b32 s41, v255, 7
	v_readlane_b32 s42, v255, 8
	v_readlane_b32 s43, v255, 9
	s_add_u32 s7, s6, 0x5000
	s_mul_hi_u32 s9, s7, 0x66666667
	s_lshr_b32 s9, s9, 12
	s_mul_i32 s10, s9, 0x2800
	s_sub_u32 s10, s7, s10
	s_sub_u32 s9, 3, s9
	s_cmp_lt_u32 s10, 0x2000
	s_cselect_b64 s[12:13], -1, 0
	s_cselect_b32 s11, 0, 0x2000
	s_cselect_b32 s14, 7, 5
	s_cselect_b32 s15, 15, 13
	s_cselect_b32 s16, 26, 24
	s_cselect_b32 s17, 25, 23
	s_cselect_b32 s20, s84, s92
	s_cselect_b32 s21, s85, s93
	s_cselect_b32 s22, s40, s42
	s_cselect_b32 s23, s41, s43
	s_sub_u32 s10, s10, s11
	s_lshr_b32 s24, s10, 3
	s_lshr_b32 s25, s24, s14
	s_lshl_b32 s26, s25, s14
	s_sub_u32 s24, s24, s26
	s_and_b32 s26, s10, 1
	s_lshl_b32 s24, s24, 1
	s_or_b32 s24, s24, s26
	s_bfe_u32 s26, s10, 0x20001
	s_lshl_b32 s25, s25, 2
	s_or_b32 s25, s25, s26
	s_lshl_b32 s25, s25, 6
	s_lshl_b32 s24, s24, 5
	s_lshl_b32 s26, s9, s16
	s_lshl_b32 s27, s25, s15
	s_add_u32 s26, s26, s27
	s_lshl_b32 s27, s24, 2
	s_add_u32 s26, s26, s27
	s_add_u32 s20, s20, s26
	s_addc_u32 s21, s21, 0
	s_lshl_b32 s28, 1, s15
	s_lshl_b32 s26, s9, s17
	s_lshl_b32 s27, s24, 12
	s_add_u32 s26, s26, s27
	s_lshl_b32 s27, s25, 1
	s_add_u32 s26, s26, s27
	s_add_u32 s22, s22, s26
	s_addc_u32 s23, s23, 0
	s_lshl_b32 s26, s9, 13
	s_lshl_b32 s27, s25, 2
	s_add_u32 s26, s26, s27
	s_add_u32 s30, s82, s26
	s_addc_u32 s31, s83, 0
	v_cndmask_b32_e64 v6, v3, v2, s[12:13]
	global_load_dwordx4 v[48:51], v4, s[30:31]
	global_load_dwordx4 v[52:55], v4, s[30:31] offset:16
	global_load_dwordx4 v[16:19], v6, s[20:21] nt
	s_add_u32 s20, s20, s28
	s_addc_u32 s21, s21, 0
	global_load_dwordx4 v[20:23], v6, s[20:21] nt
	s_add_u32 s20, s20, s28
	s_addc_u32 s21, s21, 0
	global_load_dwordx4 v[24:27], v6, s[20:21] nt
	s_add_u32 s20, s20, s28
	s_addc_u32 s21, s21, 0
	global_load_dwordx4 v[28:31], v6, s[20:21] nt
	s_add_u32 s20, s20, s28
	s_addc_u32 s21, s21, 0
	global_load_dwordx4 v[32:35], v6, s[20:21] nt
	s_add_u32 s20, s20, s28
	s_addc_u32 s21, s21, 0
	global_load_dwordx4 v[36:39], v6, s[20:21] nt
	s_add_u32 s20, s20, s28
	s_addc_u32 s21, s21, 0
	global_load_dwordx4 v[40:43], v6, s[20:21] nt
	s_add_u32 s20, s20, s28
	s_addc_u32 s21, s21, 0
	global_load_dwordx4 v[44:47], v6, s[20:21] nt
	s_lshr_b32 s47, s7, 11
	s_cmp_eq_u32 s47, 13
	s_mov_b32 s47, 0x800
	s_cselect_b32 s47, 0x1000, s47
	s_add_u32 s46, s7, s47
	s_cmp_lt_u32 s46, 0xa000
	s_cbranch_scc0 .Lp0_nob0
	s_mul_hi_u32 s9, s46, 0x66666667
	s_lshr_b32 s9, s9, 12
	s_mul_i32 s10, s9, 0x2800
	s_sub_u32 s10, s46, s10
	s_sub_u32 s9, 3, s9
	s_cmp_lt_u32 s10, 0x2000
	s_cselect_b64 s[32:33], -1, 0
	s_cselect_b32 s11, 0, 0x2000
	s_cselect_b32 s14, 7, 5
	s_cselect_b32 s15, 15, 13
	s_cselect_b32 s16, 26, 24
	s_cselect_b32 s17, 25, 23
	s_cselect_b32 s38, s84, s92
	s_cselect_b32 s39, s85, s93
	s_cselect_b32 s34, s40, s42
	s_cselect_b32 s35, s41, s43
	s_sub_u32 s10, s10, s11
	s_lshr_b32 s24, s10, 3
	s_lshr_b32 s25, s24, s14
	s_lshl_b32 s26, s25, s14
	s_sub_u32 s24, s24, s26
	s_and_b32 s26, s10, 1
	s_lshl_b32 s24, s24, 1
	s_or_b32 s24, s24, s26
	s_bfe_u32 s26, s10, 0x20001
	s_lshl_b32 s25, s25, 2
	s_or_b32 s25, s25, s26
	s_lshl_b32 s25, s25, 6
	s_lshl_b32 s24, s24, 5
	s_lshl_b32 s26, s9, s16
	s_lshl_b32 s27, s25, s15
	s_add_u32 s26, s26, s27
	s_lshl_b32 s27, s24, 2
	s_add_u32 s26, s26, s27
	s_add_u32 s38, s38, s26
	s_addc_u32 s39, s39, 0
	s_lshl_b32 s29, 1, s15
	s_lshl_b32 s26, s9, s17
	s_lshl_b32 s27, s24, 12
	s_add_u32 s26, s26, s27
	s_lshl_b32 s27, s25, 1
	s_add_u32 s26, s26, s27
	s_add_u32 s34, s34, s26
	s_addc_u32 s35, s35, 0
	s_lshl_b32 s26, s9, 13
	s_lshl_b32 s27, s25, 2
	s_add_u32 s26, s26, s27
	s_add_u32 s44, s82, s26
	s_addc_u32 s45, s83, 0
	v_cndmask_b32_e64 v7, v3, v2, s[32:33]
	global_load_dwordx4 v[96:99], v4, s[44:45]
	global_load_dwordx4 v[100:103], v4, s[44:45] offset:16
	global_load_dwordx4 v[64:67], v7, s[38:39] nt
	s_add_u32 s38, s38, s29
	s_addc_u32 s39, s39, 0
	global_load_dwordx4 v[68:71], v7, s[38:39] nt
	s_add_u32 s38, s38, s29
	s_addc_u32 s39, s39, 0
	global_load_dwordx4 v[72:75], v7, s[38:39] nt
	s_add_u32 s38, s38, s29
	s_addc_u32 s39, s39, 0
	global_load_dwordx4 v[76:79], v7, s[38:39] nt
	s_add_u32 s38, s38, s29
	s_addc_u32 s39, s39, 0
	global_load_dwordx4 v[80:83], v7, s[38:39] nt
	s_add_u32 s38, s38, s29
	s_addc_u32 s39, s39, 0
	global_load_dwordx4 v[84:87], v7, s[38:39] nt
	s_add_u32 s38, s38, s29
	s_addc_u32 s39, s39, 0
	global_load_dwordx4 v[88:91], v7, s[38:39] nt
	s_add_u32 s38, s38, s29
	s_addc_u32 s39, s39, 0
	global_load_dwordx4 v[92:95], v7, s[38:39] nt
	s_waitcnt vmcnt(10)
	s_branch .Lp0_loop

.Lp0_nomul_a:
	v_cvt_pk_bf16_f32 v112, v16, v20
	v_cvt_pk_bf16_f32 v113, v24, v28
	v_cvt_pk_bf16_f32 v114, v32, v36
	v_cvt_pk_bf16_f32 v115, v40, v44
	v_cvt_pk_bf16_f32 v116, v17, v21
	v_cvt_pk_bf16_f32 v117, v25, v29
	v_cvt_pk_bf16_f32 v118, v33, v37
	v_cvt_pk_bf16_f32 v119, v41, v45
	v_cvt_pk_bf16_f32 v120, v18, v22
	v_cvt_pk_bf16_f32 v121, v26, v30
	v_cvt_pk_bf16_f32 v122, v34, v38
	v_cvt_pk_bf16_f32 v123, v42, v46
	v_cvt_pk_bf16_f32 v124, v19, v23
	v_cvt_pk_bf16_f32 v125, v27, v31
	v_cvt_pk_bf16_f32 v126, v35, v39
	v_cvt_pk_bf16_f32 v127, v43, v47
	global_store_dwordx4 v5, v[112:115], s[22:23]
	s_add_u32 s22, s22, 0x1000
	s_addc_u32 s23, s23, 0
	global_store_dwordx4 v5, v[116:119], s[22:23]
	s_add_u32 s22, s22, 0x1000
	s_addc_u32 s23, s23, 0
	global_store_dwordx4 v5, v[120:123], s[22:23]
	s_add_u32 s22, s22, 0x1000
	s_addc_u32 s23, s23, 0
	global_store_dwordx4 v5, v[124:127], s[22:23]
	s_lshr_b32 s47, s46, 11
	s_cmp_eq_u32 s47, 13
	s_mov_b32 s47, 0x800
	s_cselect_b32 s47, 0x1000, s47
	s_add_u32 s7, s46, s47
	s_cmp_lt_u32 s46, 0xa000
	s_cbranch_scc0 .Lp0_done
	s_cmp_lt_u32 s7, 0xa000
	s_cbranch_scc0 .Lp0_noa
	s_mul_hi_u32 s9, s7, 0x66666667
	s_lshr_b32 s9, s9, 12
	s_mul_i32 s10, s9, 0x2800
	s_sub_u32 s10, s7, s10
	s_sub_u32 s9, 3, s9
	s_cmp_lt_u32 s10, 0x2000
	s_cselect_b64 s[12:13], -1, 0
	s_cselect_b32 s11, 0, 0x2000
	s_cselect_b32 s14, 7, 5
	s_cselect_b32 s15, 15, 13
	s_cselect_b32 s16, 26, 24
	s_cselect_b32 s17, 25, 23
	s_cselect_b32 s20, s84, s92
	s_cselect_b32 s21, s85, s93
	s_cselect_b32 s22, s40, s42
	s_cselect_b32 s23, s41, s43
	s_sub_u32 s10, s10, s11
	s_lshr_b32 s24, s10, 3
	s_lshr_b32 s25, s24, s14
	s_lshl_b32 s26, s25, s14
	s_sub_u32 s24, s24, s26
	s_and_b32 s26, s10, 1
	s_lshl_b32 s24, s24, 1
	s_or_b32 s24, s24, s26
	s_bfe_u32 s26, s10, 0x20001
	s_lshl_b32 s25, s25, 2
	s_or_b32 s25, s25, s26
	s_lshl_b32 s25, s25, 6
	s_lshl_b32 s24, s24, 5
	s_lshl_b32 s26, s9, s16
	s_lshl_b32 s27, s25, s15
	s_add_u32 s26, s26, s27
	s_lshl_b32 s27, s24, 2
	s_add_u32 s26, s26, s27
	s_add_u32 s20, s20, s26
	s_addc_u32 s21, s21, 0
	s_lshl_b32 s28, 1, s15
	s_lshl_b32 s26, s9, s17
	s_lshl_b32 s27, s24, 12
	s_add_u32 s26, s26, s27
	s_lshl_b32 s27, s25, 1
	s_add_u32 s26, s26, s27
	s_add_u32 s22, s22, s26
	s_addc_u32 s23, s23, 0
	s_lshl_b32 s26, s9, 13
	s_lshl_b32 s27, s25, 2
	s_add_u32 s26, s26, s27
	s_add_u32 s30, s82, s26
	s_addc_u32 s31, s83, 0
	v_cndmask_b32_e64 v6, v3, v2, s[12:13]
	global_load_dwordx4 v[48:51], v4, s[30:31]
	global_load_dwordx4 v[52:55], v4, s[30:31] offset:16
	global_load_dwordx4 v[16:19], v6, s[20:21] nt
	s_add_u32 s20, s20, s28
	s_addc_u32 s21, s21, 0
	global_load_dwordx4 v[20:23], v6, s[20:21] nt
	s_add_u32 s20, s20, s28
	s_addc_u32 s21, s21, 0
	global_load_dwordx4 v[24:27], v6, s[20:21] nt
	s_add_u32 s20, s20, s28
	s_addc_u32 s21, s21, 0
	global_load_dwordx4 v[28:31], v6, s[20:21] nt
	s_add_u32 s20, s20, s28
	s_addc_u32 s21, s21, 0
	global_load_dwordx4 v[32:35], v6, s[20:21] nt
	s_add_u32 s20, s20, s28
	s_addc_u32 s21, s21, 0
	global_load_dwordx4 v[36:39], v6, s[20:21] nt
	s_add_u32 s20, s20, s28
	s_addc_u32 s21, s21, 0
	global_load_dwordx4 v[40:43], v6, s[20:21] nt
	s_add_u32 s20, s20, s28
	s_addc_u32 s21, s21, 0
	global_load_dwordx4 v[44:47], v6, s[20:21] nt
	s_waitcnt vmcnt(14)
	s_branch .Lp0_procb

.Lp0_nomul_b:
	v_cvt_pk_bf16_f32 v112, v64, v68
	v_cvt_pk_bf16_f32 v113, v72, v76
	v_cvt_pk_bf16_f32 v114, v80, v84
	v_cvt_pk_bf16_f32 v115, v88, v92
	v_cvt_pk_bf16_f32 v116, v65, v69
	v_cvt_pk_bf16_f32 v117, v73, v77
	v_cvt_pk_bf16_f32 v118, v81, v85
	v_cvt_pk_bf16_f32 v119, v89, v93
	v_cvt_pk_bf16_f32 v120, v66, v70
	v_cvt_pk_bf16_f32 v121, v74, v78
	v_cvt_pk_bf16_f32 v122, v82, v86
	v_cvt_pk_bf16_f32 v123, v90, v94
	v_cvt_pk_bf16_f32 v124, v67, v71
	v_cvt_pk_bf16_f32 v125, v75, v79
	v_cvt_pk_bf16_f32 v126, v83, v87
	v_cvt_pk_bf16_f32 v127, v91, v95
	global_store_dwordx4 v5, v[112:115], s[34:35]
	s_add_u32 s34, s34, 0x1000
	s_addc_u32 s35, s35, 0
	global_store_dwordx4 v5, v[116:119], s[34:35]
	s_add_u32 s34, s34, 0x1000
	s_addc_u32 s35, s35, 0
	global_store_dwordx4 v5, v[120:123], s[34:35]
	s_add_u32 s34, s34, 0x1000
	s_addc_u32 s35, s35, 0
	global_store_dwordx4 v5, v[124:127], s[34:35]
	s_lshr_b32 s47, s7, 11
	s_cmp_eq_u32 s47, 13
	s_mov_b32 s47, 0x800
	s_cselect_b32 s47, 0x1000, s47
	s_add_u32 s46, s7, s47
	s_cmp_lt_u32 s7, 0xa000
	s_cbranch_scc0 .Lp0_done
	s_cmp_lt_u32 s46, 0xa000
	s_cbranch_scc0 .Lp0_nob
	s_mul_hi_u32 s9, s46, 0x66666667
	s_lshr_b32 s9, s9, 12
	s_mul_i32 s10, s9, 0x2800
	s_sub_u32 s10, s46, s10
	s_sub_u32 s9, 3, s9
	s_cmp_lt_u32 s10, 0x2000
	s_cselect_b64 s[32:33], -1, 0
	s_cselect_b32 s11, 0, 0x2000
	s_cselect_b32 s14, 7, 5
	s_cselect_b32 s15, 15, 13
	s_cselect_b32 s16, 26, 24
	s_cselect_b32 s17, 25, 23
	s_cselect_b32 s38, s84, s92
	s_cselect_b32 s39, s85, s93
	s_cselect_b32 s34, s40, s42
	s_cselect_b32 s35, s41, s43
	s_sub_u32 s10, s10, s11
	s_lshr_b32 s24, s10, 3
	s_lshr_b32 s25, s24, s14
	s_lshl_b32 s26, s25, s14
	s_sub_u32 s24, s24, s26
	s_and_b32 s26, s10, 1
	s_lshl_b32 s24, s24, 1
	s_or_b32 s24, s24, s26
	s_bfe_u32 s26, s10, 0x20001
	s_lshl_b32 s25, s25, 2
	s_or_b32 s25, s25, s26
	s_lshl_b32 s25, s25, 6
	s_lshl_b32 s24, s24, 5
	s_lshl_b32 s26, s9, s16
	s_lshl_b32 s27, s25, s15
	s_add_u32 s26, s26, s27
	s_lshl_b32 s27, s24, 2
	s_add_u32 s26, s26, s27
	s_add_u32 s38, s38, s26
	s_addc_u32 s39, s39, 0
	s_lshl_b32 s29, 1, s15
	s_lshl_b32 s26, s9, s17
	s_lshl_b32 s27, s24, 12
	s_add_u32 s26, s26, s27
	s_lshl_b32 s27, s25, 1
	s_add_u32 s26, s26, s27
	s_add_u32 s34, s34, s26
	s_addc_u32 s35, s35, 0
	s_lshl_b32 s26, s9, 13
	s_lshl_b32 s27, s25, 2
	s_add_u32 s26, s26, s27
	s_add_u32 s44, s82, s26
	s_addc_u32 s45, s83, 0
	v_cndmask_b32_e64 v7, v3, v2, s[32:33]
	global_load_dwordx4 v[96:99], v4, s[44:45]
	global_load_dwordx4 v[100:103], v4, s[44:45] offset:16
	global_load_dwordx4 v[64:67], v7, s[38:39] nt
	s_add_u32 s38, s38, s29
	s_addc_u32 s39, s39, 0
	global_load_dwordx4 v[68:71], v7, s[38:39] nt
	s_add_u32 s38, s38, s29
	s_addc_u32 s39, s39, 0
	global_load_dwordx4 v[72:75], v7, s[38:39] nt
	s_add_u32 s38, s38, s29
	s_addc_u32 s39, s39, 0
	global_load_dwordx4 v[76:79], v7, s[38:39] nt
	s_add_u32 s38, s38, s29
	s_addc_u32 s39, s39, 0
	global_load_dwordx4 v[80:83], v7, s[38:39] nt
	s_add_u32 s38, s38, s29
	s_addc_u32 s39, s39, 0
	global_load_dwordx4 v[84:87], v7, s[38:39] nt
	s_add_u32 s38, s38, s29
	s_addc_u32 s39, s39, 0
	global_load_dwordx4 v[88:91], v7, s[38:39] nt
	s_add_u32 s38, s38, s29
	s_addc_u32 s39, s39, 0
	global_load_dwordx4 v[92:95], v7, s[38:39] nt
	s_waitcnt vmcnt(14)
	s_branch .Lp0_loop

.LBB0_244:
	s_or_b64 exec, exec, s[2:3]
	s_lshl_b32 s0, s78, 9
	s_mov_b32 s1, s63
	s_mov_b32 s2, s0
	v_writelane_b32 v255, s2, 45
	s_lshl_b64 s[0:1], s[0:1], 2
	s_add_u32 s86, s56, s0
	v_writelane_b32 v255, s3, 46
	s_addc_u32 s87, s57, s1
	v_readlane_b32 s2, v255, 14
	s_add_u32 s83, s2, s0
	v_readlane_b32 s0, v255, 15
	s_addc_u32 s82, s0, s1
	s_lshl_b32 s62, s78, 7
	v_readlane_b32 s0, v255, 26
	s_lshl_b64 s[84:85], s[62:63], 2
	v_readlane_b32 s6, v255, 32
	v_readlane_b32 s7, v255, 33
	s_add_u32 s88, s6, s84
	v_readlane_b32 s8, v255, 34
	s_addc_u32 s89, s7, s85
	v_readlane_b32 s1, v255, 27
	v_readlane_b32 s9, v255, 35
	s_add_u32 s90, s8, s84
	v_readlane_b32 s10, v255, 36
	s_addc_u32 s91, s9, s85
	s_mul_i32 s1, s78, 0x2800
	v_readlane_b32 s11, v255, 37
	s_mul_hi_u32 s0, s78, 0x2800
	s_add_u32 s92, s10, s1
	v_mov_b32_e32 v0, v243
	s_waitcnt lgkmcnt(0)
	s_barrier
	s_addc_u32 s93, s11, s0
	v_readlane_b32 s6, v255, 59
	s_cmp_lt_u32 s78, 3
	s_cbranch_scc0 .Lcv_skip
	s_cmp_lt_u32 s6, 0x400
	s_cbranch_scc0 .Lcv_skip
	v_readlane_b32 s2, v255, 57
	v_readlane_b32 s3, v255, 58
	v_readlane_b32 s4, v255, 53
	v_readlane_b32 s5, v255, 54
	v_readlane_b32 s18, v255, 60
	v_readlane_b32 s19, v255, 61
	v_readlane_b32 s40, v255, 6
	v_readlane_b32 s41, v255, 7
	v_readlane_b32 s42, v255, 8
	v_readlane_b32 s43, v255, 9
	v_and_b32_e32 v12, 63, v243
	v_lshrrev_b32_e32 v6, 3, v12
	v_and_b32_e32 v7, 7, v12
	v_lshlrev_b32_e32 v8, 4, v7
	v_lshl_or_b32 v2, v6, 18, v8
	v_lshl_or_b32 v3, v6, 16, v8
	v_lshlrev_b32_e32 v11, 5, v6
	v_lshlrev_b32_e32 v9, 4, v6
	v_lshl_or_b32 v5, v7, 14, v9
	s_sub_u32 s47, 1, s78
	s_mul_i32 s47, s47, 0x2800
	s_add_u32 s7, s47, s6
	s_add_u32 s59, s47, 0x2000
	s_add_u32 s47, s6, 0x2000
	s_sub_u32 s58, 3, s78
	s_mul_i32 s58, s58, 0x2800
	s_cmp_eq_u32 s78, 2
	s_cselect_b32 s59, 0x80000000, s59
	s_cselect_b32 s7, s47, s7
	s_mul_hi_u32 s9, s7, 0x66666667
	s_lshr_b32 s9, s9, 12
	s_mul_i32 s10, s9, 0x2800
	s_sub_u32 s10, s7, s10
	s_sub_u32 s9, 3, s9
	s_cmp_lt_u32 s10, 0x2000
	s_cselect_b64 s[12:13], -1, 0
	s_cselect_b32 s11, 0, 0x2000
	s_cselect_b32 s14, 7, 5
	s_cselect_b32 s15, 15, 13
	s_cselect_b32 s48, 26, 24
	s_cselect_b32 s17, 25, 23
	s_cselect_b32 s20, s4, s18
	s_cselect_b32 s21, s5, s19
	s_cselect_b32 s22, s40, s42
	s_cselect_b32 s23, s41, s43
	s_sub_u32 s10, s10, s11
	s_lshr_b32 s24, s10, 3
	s_lshr_b32 s25, s24, s14
	s_lshl_b32 s26, s25, s14
	s_sub_u32 s24, s24, s26
	s_and_b32 s26, s10, 1
	s_lshl_b32 s24, s24, 1
	s_or_b32 s24, s24, s26
	s_bfe_u32 s26, s10, 0x20001
	s_lshl_b32 s25, s25, 2
	s_or_b32 s25, s25, s26
	s_lshl_b32 s25, s25, 6
	s_lshl_b32 s24, s24, 5
	s_lshl_b32 s26, s9, s48
	s_lshl_b32 s27, s25, s15
	s_add_u32 s26, s26, s27
	s_lshl_b32 s27, s24, 2
	s_add_u32 s26, s26, s27
	s_add_u32 s20, s20, s26
	s_addc_u32 s21, s21, 0
	s_lshl_b32 s28, 1, s15
	s_lshl_b32 s26, s9, s17
	s_lshl_b32 s27, s24, 12
	s_add_u32 s26, s26, s27
	s_lshl_b32 s27, s25, 1
	s_add_u32 s26, s26, s27
	s_add_u32 s22, s22, s26
	s_addc_u32 s23, s23, 0
	s_lshl_b32 s26, s9, 13
	s_lshl_b32 s27, s25, 2
	s_add_u32 s26, s26, s27
	s_add_u32 s30, s2, s26
	s_addc_u32 s31, s3, 0
	v_cndmask_b32_e64 v6, v3, v2, s[12:13]
	global_load_dwordx4 v[48:51], v11, s[30:31]
	global_load_dwordx4 v[52:55], v11, s[30:31] offset:16
	global_load_dwordx4 v[16:19], v6, s[20:21] nt
	s_add_u32 s20, s20, s28
	s_addc_u32 s21, s21, 0
	global_load_dwordx4 v[20:23], v6, s[20:21] nt
	s_add_u32 s20, s20, s28
	s_addc_u32 s21, s21, 0
	global_load_dwordx4 v[24:27], v6, s[20:21] nt
	s_add_u32 s20, s20, s28
	s_addc_u32 s21, s21, 0
	global_load_dwordx4 v[28:31], v6, s[20:21] nt
	s_add_u32 s20, s20, s28
	s_addc_u32 s21, s21, 0
	global_load_dwordx4 v[32:35], v6, s[20:21] nt
	s_add_u32 s20, s20, s28
	s_addc_u32 s21, s21, 0
	global_load_dwordx4 v[36:39], v6, s[20:21] nt
	s_add_u32 s20, s20, s28
	s_addc_u32 s21, s21, 0
	global_load_dwordx4 v[40:43], v6, s[20:21] nt
	s_add_u32 s20, s20, s28
	s_addc_u32 s21, s21, 0
	global_load_dwordx4 v[44:47], v6, s[20:21] nt
	s_add_u32 s46, s7, 0x400
	s_sub_u32 s47, s46, s59
	s_cmp_lt_u32 s47, 0x400
	s_cselect_b32 s47, 0x2800, 0
	s_add_u32 s46, s46, s47
	s_cmp_lt_u32 s46, s58
	s_cbranch_scc0 .Lcv_nob0
	s_mul_hi_u32 s9, s46, 0x66666667
	s_lshr_b32 s9, s9, 12
	s_mul_i32 s10, s9, 0x2800
	s_sub_u32 s10, s46, s10
	s_sub_u32 s9, 3, s9
	s_cmp_lt_u32 s10, 0x2000
	s_cselect_b64 s[50:51], -1, 0
	s_cselect_b32 s11, 0, 0x2000
	s_cselect_b32 s14, 7, 5
	s_cselect_b32 s15, 15, 13
	s_cselect_b32 s48, 26, 24
	s_cselect_b32 s17, 25, 23
	s_cselect_b32 s38, s4, s18
	s_cselect_b32 s39, s5, s19
	s_cselect_b32 s34, s40, s42
	s_cselect_b32 s35, s41, s43
	s_sub_u32 s10, s10, s11
	s_lshr_b32 s24, s10, 3
	s_lshr_b32 s25, s24, s14
	s_lshl_b32 s26, s25, s14
	s_sub_u32 s24, s24, s26
	s_and_b32 s26, s10, 1
	s_lshl_b32 s24, s24, 1
	s_or_b32 s24, s24, s26
	s_bfe_u32 s26, s10, 0x20001
	s_lshl_b32 s25, s25, 2
	s_or_b32 s25, s25, s26
	s_lshl_b32 s25, s25, 6
	s_lshl_b32 s24, s24, 5
	s_lshl_b32 s26, s9, s48
	s_lshl_b32 s27, s25, s15
	s_add_u32 s26, s26, s27
	s_lshl_b32 s27, s24, 2
	s_add_u32 s26, s26, s27
	s_add_u32 s38, s38, s26
	s_addc_u32 s39, s39, 0
	s_lshl_b32 s29, 1, s15
	s_lshl_b32 s26, s9, s17
	s_lshl_b32 s27, s24, 12
	s_add_u32 s26, s26, s27
	s_lshl_b32 s27, s25, 1
	s_add_u32 s26, s26, s27
	s_add_u32 s34, s34, s26
	s_addc_u32 s35, s35, 0
	s_lshl_b32 s26, s9, 13
	s_lshl_b32 s27, s25, 2
	s_add_u32 s26, s26, s27
	s_add_u32 s56, s2, s26
	s_addc_u32 s57, s3, 0
	v_cndmask_b32_e64 v7, v3, v2, s[50:51]
	global_load_dwordx4 v[96:99], v11, s[56:57]
	global_load_dwordx4 v[100:103], v11, s[56:57] offset:16
	global_load_dwordx4 v[64:67], v7, s[38:39] nt
	s_add_u32 s38, s38, s29
	s_addc_u32 s39, s39, 0
	global_load_dwordx4 v[68:71], v7, s[38:39] nt
	s_add_u32 s38, s38, s29
	s_addc_u32 s39, s39, 0
	global_load_dwordx4 v[72:75], v7, s[38:39] nt
	s_add_u32 s38, s38, s29
	s_addc_u32 s39, s39, 0
	global_load_dwordx4 v[76:79], v7, s[38:39] nt
	s_add_u32 s38, s38, s29
	s_addc_u32 s39, s39, 0
	global_load_dwordx4 v[80:83], v7, s[38:39] nt
	s_add_u32 s38, s38, s29
	s_addc_u32 s39, s39, 0
	global_load_dwordx4 v[84:87], v7, s[38:39] nt
	s_add_u32 s38, s38, s29
	s_addc_u32 s39, s39, 0
	global_load_dwordx4 v[88:91], v7, s[38:39] nt
	s_add_u32 s38, s38, s29
	s_addc_u32 s39, s39, 0
	global_load_dwordx4 v[92:95], v7, s[38:39] nt
	s_waitcnt vmcnt(10)
	s_branch .Lcv_loop

.Lcv_nomul_a:
	v_cvt_pk_bf16_f32 v112, v16, v20
	v_cvt_pk_bf16_f32 v113, v24, v28
	v_cvt_pk_bf16_f32 v114, v32, v36
	v_cvt_pk_bf16_f32 v115, v40, v44
	v_cvt_pk_bf16_f32 v116, v17, v21
	v_cvt_pk_bf16_f32 v117, v25, v29
	v_cvt_pk_bf16_f32 v118, v33, v37
	v_cvt_pk_bf16_f32 v119, v41, v45
	v_cvt_pk_bf16_f32 v120, v18, v22
	v_cvt_pk_bf16_f32 v121, v26, v30
	v_cvt_pk_bf16_f32 v122, v34, v38
	v_cvt_pk_bf16_f32 v123, v42, v46
	v_cvt_pk_bf16_f32 v124, v19, v23
	v_cvt_pk_bf16_f32 v125, v27, v31
	v_cvt_pk_bf16_f32 v126, v35, v39
	v_cvt_pk_bf16_f32 v127, v43, v47
	global_store_dwordx4 v5, v[112:115], s[22:23]
	s_add_u32 s22, s22, 0x1000
	s_addc_u32 s23, s23, 0
	global_store_dwordx4 v5, v[116:119], s[22:23]
	s_add_u32 s22, s22, 0x1000
	s_addc_u32 s23, s23, 0
	global_store_dwordx4 v5, v[120:123], s[22:23]
	s_add_u32 s22, s22, 0x1000
	s_addc_u32 s23, s23, 0
	global_store_dwordx4 v5, v[124:127], s[22:23]
	s_add_u32 s7, s46, 0x400
	s_sub_u32 s47, s7, s59
	s_cmp_lt_u32 s47, 0x400
	s_cselect_b32 s47, 0x2800, 0
	s_add_u32 s7, s7, s47
	s_cmp_lt_u32 s46, s58
	s_cbranch_scc0 .Lcv_done
	s_cmp_lt_u32 s7, s58
	s_cbranch_scc0 .Lcv_noa
	s_mul_hi_u32 s9, s7, 0x66666667
	s_lshr_b32 s9, s9, 12
	s_mul_i32 s10, s9, 0x2800
	s_sub_u32 s10, s7, s10
	s_sub_u32 s9, 3, s9
	s_cmp_lt_u32 s10, 0x2000
	s_cselect_b64 s[12:13], -1, 0
	s_cselect_b32 s11, 0, 0x2000
	s_cselect_b32 s14, 7, 5
	s_cselect_b32 s15, 15, 13
	s_cselect_b32 s48, 26, 24
	s_cselect_b32 s17, 25, 23
	s_cselect_b32 s20, s4, s18
	s_cselect_b32 s21, s5, s19
	s_cselect_b32 s22, s40, s42
	s_cselect_b32 s23, s41, s43
	s_sub_u32 s10, s10, s11
	s_lshr_b32 s24, s10, 3
	s_lshr_b32 s25, s24, s14
	s_lshl_b32 s26, s25, s14
	s_sub_u32 s24, s24, s26
	s_and_b32 s26, s10, 1
	s_lshl_b32 s24, s24, 1
	s_or_b32 s24, s24, s26
	s_bfe_u32 s26, s10, 0x20001
	s_lshl_b32 s25, s25, 2
	s_or_b32 s25, s25, s26
	s_lshl_b32 s25, s25, 6
	s_lshl_b32 s24, s24, 5
	s_lshl_b32 s26, s9, s48
	s_lshl_b32 s27, s25, s15
	s_add_u32 s26, s26, s27
	s_lshl_b32 s27, s24, 2
	s_add_u32 s26, s26, s27
	s_add_u32 s20, s20, s26
	s_addc_u32 s21, s21, 0
	s_lshl_b32 s28, 1, s15
	s_lshl_b32 s26, s9, s17
	s_lshl_b32 s27, s24, 12
	s_add_u32 s26, s26, s27
	s_lshl_b32 s27, s25, 1
	s_add_u32 s26, s26, s27
	s_add_u32 s22, s22, s26
	s_addc_u32 s23, s23, 0
	s_lshl_b32 s26, s9, 13
	s_lshl_b32 s27, s25, 2
	s_add_u32 s26, s26, s27
	s_add_u32 s30, s2, s26
	s_addc_u32 s31, s3, 0
	v_cndmask_b32_e64 v6, v3, v2, s[12:13]
	global_load_dwordx4 v[48:51], v11, s[30:31]
	global_load_dwordx4 v[52:55], v11, s[30:31] offset:16
	global_load_dwordx4 v[16:19], v6, s[20:21] nt
	s_add_u32 s20, s20, s28
	s_addc_u32 s21, s21, 0
	global_load_dwordx4 v[20:23], v6, s[20:21] nt
	s_add_u32 s20, s20, s28
	s_addc_u32 s21, s21, 0
	global_load_dwordx4 v[24:27], v6, s[20:21] nt
	s_add_u32 s20, s20, s28
	s_addc_u32 s21, s21, 0
	global_load_dwordx4 v[28:31], v6, s[20:21] nt
	s_add_u32 s20, s20, s28
	s_addc_u32 s21, s21, 0
	global_load_dwordx4 v[32:35], v6, s[20:21] nt
	s_add_u32 s20, s20, s28
	s_addc_u32 s21, s21, 0
	global_load_dwordx4 v[36:39], v6, s[20:21] nt
	s_add_u32 s20, s20, s28
	s_addc_u32 s21, s21, 0
	global_load_dwordx4 v[40:43], v6, s[20:21] nt
	s_add_u32 s20, s20, s28
	s_addc_u32 s21, s21, 0
	global_load_dwordx4 v[44:47], v6, s[20:21] nt
	s_waitcnt vmcnt(14)
	s_branch .Lcv_procb

.Lcv_procb:
	s_cmp_eq_u64 s[50:51], 0
	s_cbranch_scc1 .Lcv_nomul_b
	v_mul_f32_e32 v64, v64, v96
	v_mul_f32_e32 v65, v65, v96
	v_mul_f32_e32 v66, v66, v96
	v_mul_f32_e32 v67, v67, v96
	v_mul_f32_e32 v68, v68, v97
	v_mul_f32_e32 v69, v69, v97
	v_mul_f32_e32 v70, v70, v97
	v_mul_f32_e32 v71, v71, v97
	v_mul_f32_e32 v72, v72, v98
	v_mul_f32_e32 v73, v73, v98
	v_mul_f32_e32 v74, v74, v98
	v_mul_f32_e32 v75, v75, v98
	v_mul_f32_e32 v76, v76, v99
	v_mul_f32_e32 v77, v77, v99
	v_mul_f32_e32 v78, v78, v99
	v_mul_f32_e32 v79, v79, v99
	v_mul_f32_e32 v80, v80, v100
	v_mul_f32_e32 v81, v81, v100
	v_mul_f32_e32 v82, v82, v100
	v_mul_f32_e32 v83, v83, v100
	v_mul_f32_e32 v84, v84, v101
	v_mul_f32_e32 v85, v85, v101
	v_mul_f32_e32 v86, v86, v101
	v_mul_f32_e32 v87, v87, v101
	v_mul_f32_e32 v88, v88, v102
	v_mul_f32_e32 v89, v89, v102
	v_mul_f32_e32 v90, v90, v102
	v_mul_f32_e32 v91, v91, v102
	v_mul_f32_e32 v92, v92, v103
	v_mul_f32_e32 v93, v93, v103
	v_mul_f32_e32 v94, v94, v103
	v_mul_f32_e32 v95, v95, v103
.Lcv_nomul_b:
	v_cvt_pk_bf16_f32 v112, v64, v68
	v_cvt_pk_bf16_f32 v113, v72, v76
	v_cvt_pk_bf16_f32 v114, v80, v84
	v_cvt_pk_bf16_f32 v115, v88, v92
	v_cvt_pk_bf16_f32 v116, v65, v69
	v_cvt_pk_bf16_f32 v117, v73, v77
	v_cvt_pk_bf16_f32 v118, v81, v85
	v_cvt_pk_bf16_f32 v119, v89, v93
	v_cvt_pk_bf16_f32 v120, v66, v70
	v_cvt_pk_bf16_f32 v121, v74, v78
	v_cvt_pk_bf16_f32 v122, v82, v86
	v_cvt_pk_bf16_f32 v123, v90, v94
	v_cvt_pk_bf16_f32 v124, v67, v71
	v_cvt_pk_bf16_f32 v125, v75, v79
	v_cvt_pk_bf16_f32 v126, v83, v87
	v_cvt_pk_bf16_f32 v127, v91, v95
	global_store_dwordx4 v5, v[112:115], s[34:35]
	s_add_u32 s34, s34, 0x1000
	s_addc_u32 s35, s35, 0
	global_store_dwordx4 v5, v[116:119], s[34:35]
	s_add_u32 s34, s34, 0x1000
	s_addc_u32 s35, s35, 0
	global_store_dwordx4 v5, v[120:123], s[34:35]
	s_add_u32 s34, s34, 0x1000
	s_addc_u32 s35, s35, 0
	global_store_dwordx4 v5, v[124:127], s[34:35]
	s_add_u32 s46, s7, 0x400
	s_sub_u32 s47, s46, s59
	s_cmp_lt_u32 s47, 0x400
	s_cselect_b32 s47, 0x2800, 0
	s_add_u32 s46, s46, s47
	s_cmp_lt_u32 s7, s58
	s_cbranch_scc0 .Lcv_done
	s_cmp_lt_u32 s46, s58
	s_cbranch_scc0 .Lcv_nob
	s_mul_hi_u32 s9, s46, 0x66666667
	s_lshr_b32 s9, s9, 12
	s_mul_i32 s10, s9, 0x2800
	s_sub_u32 s10, s46, s10
	s_sub_u32 s9, 3, s9
	s_cmp_lt_u32 s10, 0x2000
	s_cselect_b64 s[50:51], -1, 0
	s_cselect_b32 s11, 0, 0x2000
	s_cselect_b32 s14, 7, 5
	s_cselect_b32 s15, 15, 13
	s_cselect_b32 s48, 26, 24
	s_cselect_b32 s17, 25, 23
	s_cselect_b32 s38, s4, s18
	s_cselect_b32 s39, s5, s19
	s_cselect_b32 s34, s40, s42
	s_cselect_b32 s35, s41, s43
	s_sub_u32 s10, s10, s11
	s_lshr_b32 s24, s10, 3
	s_lshr_b32 s25, s24, s14
	s_lshl_b32 s26, s25, s14
	s_sub_u32 s24, s24, s26
	s_and_b32 s26, s10, 1
	s_lshl_b32 s24, s24, 1
	s_or_b32 s24, s24, s26
	s_bfe_u32 s26, s10, 0x20001
	s_lshl_b32 s25, s25, 2
	s_or_b32 s25, s25, s26
	s_lshl_b32 s25, s25, 6
	s_lshl_b32 s24, s24, 5
	s_lshl_b32 s26, s9, s48
	s_lshl_b32 s27, s25, s15
	s_add_u32 s26, s26, s27
	s_lshl_b32 s27, s24, 2
	s_add_u32 s26, s26, s27
	s_add_u32 s38, s38, s26
	s_addc_u32 s39, s39, 0
	s_lshl_b32 s29, 1, s15
	s_lshl_b32 s26, s9, s17
	s_lshl_b32 s27, s24, 12
	s_add_u32 s26, s26, s27
	s_lshl_b32 s27, s25, 1
	s_add_u32 s26, s26, s27
	s_add_u32 s34, s34, s26
	s_addc_u32 s35, s35, 0
	s_lshl_b32 s26, s9, 13
	s_lshl_b32 s27, s25, 2
	s_add_u32 s26, s26, s27
	s_add_u32 s56, s2, s26
	s_addc_u32 s57, s3, 0
	v_cndmask_b32_e64 v7, v3, v2, s[50:51]
	global_load_dwordx4 v[96:99], v11, s[56:57]
	global_load_dwordx4 v[100:103], v11, s[56:57] offset:16
	global_load_dwordx4 v[64:67], v7, s[38:39] nt
	s_add_u32 s38, s38, s29
	s_addc_u32 s39, s39, 0
	global_load_dwordx4 v[68:71], v7, s[38:39] nt
	s_add_u32 s38, s38, s29
	s_addc_u32 s39, s39, 0
	global_load_dwordx4 v[72:75], v7, s[38:39] nt
	s_add_u32 s38, s38, s29
	s_addc_u32 s39, s39, 0
	global_load_dwordx4 v[76:79], v7, s[38:39] nt
	s_add_u32 s38, s38, s29
	s_addc_u32 s39, s39, 0
	global_load_dwordx4 v[80:83], v7, s[38:39] nt
	s_add_u32 s38, s38, s29
	s_addc_u32 s39, s39, 0
	global_load_dwordx4 v[84:87], v7, s[38:39] nt
	s_add_u32 s38, s38, s29
	s_addc_u32 s39, s39, 0
	global_load_dwordx4 v[88:91], v7, s[38:39] nt
	s_add_u32 s38, s38, s29
	s_addc_u32 s39, s39, 0
	global_load_dwordx4 v[92:95], v7, s[38:39] nt
	s_waitcnt vmcnt(14)
	s_branch .Lcv_loop
.Lcv_nob:
	s_waitcnt vmcnt(0)
	s_branch .Lcv_loop
.Lcv_done:
	s_waitcnt vmcnt(0)
.Lcv_skip:
	v_readlane_b32 s4, v255, 30
	v_and_b32_e32 v2, 63, v0
	v_readfirstlane_b32 s0, v0
	v_readlane_b32 s5, v255, 31
	s_cmp_lt_u32 s0, 64
	v_lshlrev_b32_e32 v0, 8, v2
	s_cselect_b64 s[94:95], -1, 0
	s_mov_b32 s52, 0
	s_mov_b32 s32, 0
	v_cmp_eq_u32_e64 s[10:11], 0, v2
	v_cmp_gt_u32_e64 s[4:5], 8, v2
	v_lshl_add_u64 v[180:181], s[86:87], 0, v[0:1]
	s_mov_b32 s55, s54
	s_mov_b32 s97, s54
	v_readlane_b32 s2, v255, 28
	v_readlane_b32 s3, v255, 29
	v_readlane_b32 s12, v255, 38
	v_readlane_b32 s13, v255, 39
	v_readlane_b32 s14, v255, 40
	v_readlane_b32 s15, v255, 41
	s_branch .LBB0_247
